# v73 with the B-conv vmcnt waits re-derived so the original completion points are kept
# speedup vs baseline: 1.0080x; 1.0080x over previous
; __device__ __forceinline__ unsigned pk2(float lo, float hi) { f32x2_t v = {lo, hi}; bf16x2_t b = __builtin_convertvector(v, bf16x2_t); return __builtin_bit_cast(unsigned, b); }
; __device__ __forceinline__ void conv4x8(const Params& p, int b, int c, int l0, int ch, float (&o)[4][8]) {
;     const bfu* proj = (const bfu*)(p.ws + WS_PROJ);
;     bfu* xbc = (bfu*)(p.ws + WS_XBC);
;     float w0[8], w1[8], w2[8], w3[8], cb[8];
;     ld8f32(p.conv_w + ch, w0); ld8f32(p.conv_w + 2048 + ch, w1); ld8f32(p.conv_w + 4096 + ch, w2); ld8f32(p.conv_w + 6144 + ch, w3); ld8f32(p.conv_b + ch, cb);
;     const int t0 = c * 128 + l0;
;     const size_t rowb = (size_t)b * 4096;
;     float r[7][8];
; #pragma unroll
;     for (int k = 0; k < 7; ++k) {
;         const int t = t0 - 3 + k;
;         ld8f(proj + (rowb + (t < 0 ? 0 : t)) * NPROJ + 4096 + ch, r[k]);
;         if (k < 3) {
; #pragma unroll
;             for (int j = 0; j < 8; ++j) r[k][j] = (t >= 0) ? r[k][j] : 0.f;
;         }
;     }
; __device__ __forceinline__ void ssd_s1_unit(const Params& p, int unit, unsigned char* ldsb) {
;     ...
;         conv4x8(p, b, c, l0, 1024 + g * 128 + cgrp * 8, o);
; #pragma unroll
;         for (int j = 0; j < 8; ++j) { uint2 w; w.x = pk2(o[0][j], o[1][j]); w.y = pk2(o[2][j], o[3][j]); *(uint2*)(BT + (cgrp * 8 + j) * 136 + l0) = w; }
;         conv4x8(p, b, c, l0, 1536 + g * 128 + cgrp * 8, o);
.LBB0_377:
	s_or_b64 exec, exec, s[24:25]
	v_add_u32_e32 v102, s77, v200
	s_ashr_i32 s61, s60, 31
	s_lshl_b64 s[62:63], s[60:61], 12
	v_sub_u32_e64 v80, v102, 3 clamp
	v_lshl_add_u64 v[0:1], s[62:63], 0, v[80:81]
	v_lshl_or_b32 v85, s79, 7, v201
	v_mad_u64_u32 v[2:3], s[24:25], v0, s68, v[82:83]
	v_or_b32_e32 v4, 0x400, v85
	v_mad_i32_i24 v3, v1, s68, v3
	v_lshl_add_u64 v[94:95], v[2:3], 0, s[56:57]
	v_lshlrev_b32_e32 v80, 1, v4
	v_lshl_add_u64 v[0:1], v[94:95], 0, v[80:81]
	s_waitcnt lgkmcnt(0)
	s_barrier
	global_load_dwordx4 v[32:35], v[0:1], off
	global_load_dwordx4 v[212:215], v[0:1], off offset:1024
	v_sub_u32_e64 v0, v102, 2 clamp
	v_mov_b32_e32 v1, v81
	v_lshl_add_u64 v[0:1], s[62:63], 0, v[0:1]
	v_mad_u64_u32 v[2:3], s[24:25], v0, s68, v[82:83]
	v_mad_i32_i24 v3, v1, s68, v3
	v_lshl_add_u64 v[98:99], v[2:3], 0, s[56:57]
	v_lshl_add_u64 v[0:1], v[98:99], 0, v[80:81]
	global_load_dwordx4 v[36:39], v[0:1], off
	global_load_dwordx4 v[216:219], v[0:1], off offset:1024
	v_sub_u32_e64 v0, v102, 1 clamp
	v_mov_b32_e32 v1, v81
	v_lshl_add_u64 v[0:1], s[62:63], 0, v[0:1]
	v_mad_u64_u32 v[2:3], s[24:25], v0, s68, v[82:83]
	v_mad_i32_i24 v3, v1, s68, v3
	v_lshl_add_u64 v[96:97], v[2:3], 0, s[56:57]
	v_mov_b32_e32 v103, v81
	v_lshl_add_u64 v[0:1], v[96:97], 0, v[80:81]
	v_lshl_add_u64 v[60:61], s[62:63], 0, v[102:103]
	global_load_dwordx4 v[40:43], v[0:1], off
	global_load_dwordx4 v[220:223], v[0:1], off offset:1024
	v_mad_u64_u32 v[0:1], s[24:25], v60, s68, v[82:83]
	v_mad_i32_i24 v1, v61, s68, v1
	v_lshl_add_u64 v[100:101], v[0:1], 0, s[56:57]
	v_lshl_add_u64 v[0:1], v[100:101], 0, v[80:81]
	global_load_dwordx4 v[46:49], v[0:1], off
	global_load_dwordx4 v[224:227], v[0:1], off offset:1024
	v_lshlrev_b32_e32 v116, 2, v4
	global_load_dwordx4 v[0:3], v116, s[4:5] offset:16
	global_load_dwordx4 v[12:15], v116, s[4:5]
	global_load_dwordx4 v[4:7], v116, s[50:51] offset:16
	global_load_dwordx4 v[16:19], v116, s[50:51]
	global_load_dwordx4 v[8:11], v116, s[52:53] offset:16
	global_load_dwordx4 v[20:23], v116, s[52:53]
	global_load_dwordx4 v[24:27], v116, s[36:37]
	global_load_dwordx4 v[28:31], v116, s[38:39]
	v_cmp_eq_u32_e64 s[24:25], 0, v102
	v_lshlrev_b64 v[60:61], 12, v[60:61]
	s_mul_hi_i32 s65, s60, 3
	s_mul_i32 s64, s60, 3
	v_cmp_lt_u32_e64 s[28:29], s69, v102
	s_waitcnt vmcnt(15)
	v_lshlrev_b32_e32 v44, 16, v32
	v_and_b32_e32 v32, 0xffff0000, v32
	v_lshlrev_b32_e32 v45, 16, v33
	v_and_b32_e32 v33, 0xffff0000, v33
	v_lshlrev_b32_e32 v51, 16, v34
	v_and_b32_e32 v34, 0xffff0000, v34
	v_lshlrev_b32_e32 v52, 16, v35
	v_and_b32_e32 v35, 0xffff0000, v35
	v_cndmask_b32_e64 v62, v32, 0, s[24:25]
	s_waitcnt vmcnt(13)
	v_lshlrev_b32_e32 v53, 16, v36
	v_and_b32_e32 v36, 0xffff0000, v36
	v_lshlrev_b32_e32 v54, 16, v37
	v_and_b32_e32 v37, 0xffff0000, v37
	v_lshlrev_b32_e32 v55, 16, v38
	v_and_b32_e32 v38, 0xffff0000, v38
	v_lshlrev_b32_e32 v56, 16, v39
	v_and_b32_e32 v39, 0xffff0000, v39
	v_cndmask_b32_e64 v114, v33, 0, s[24:25]
	v_cndmask_b32_e64 v126, v34, 0, s[24:25]
	v_cndmask_b32_e64 v132, v35, 0, s[24:25]
	v_cndmask_b32_e64 v129, v36, 0, s[24:25]
	v_cndmask_b32_e64 v111, v37, 0, s[24:25]
	v_cndmask_b32_e64 v67, v38, 0, s[24:25]
	v_cndmask_b32_e64 v65, v39, 0, s[24:25]
	global_load_dwordx4 v[32:35], v116, s[36:37] offset:16
	global_load_dwordx4 v[36:39], v116, s[38:39] offset:16
	s_waitcnt vmcnt(13)
	v_lshlrev_b32_e32 v57, 16, v40
	v_and_b32_e32 v40, 0xffff0000, v40
	v_lshlrev_b32_e32 v58, 16, v41
	v_and_b32_e32 v41, 0xffff0000, v41
	v_lshlrev_b32_e32 v59, 16, v42
	v_and_b32_e32 v42, 0xffff0000, v42
	v_lshlrev_b32_e32 v63, 16, v43
	v_and_b32_e32 v43, 0xffff0000, v43
	v_cndmask_b32_e64 v75, v40, 0, s[24:25]
	v_cndmask_b32_e64 v73, v41, 0, s[24:25]
	v_cndmask_b32_e64 v71, v42, 0, s[24:25]
	v_cndmask_b32_e64 v69, v43, 0, s[24:25]
	s_waitcnt vmcnt(11)
	v_lshlrev_b32_e32 v40, 16, v48
	v_and_b32_e32 v41, 0xffff0000, v48
	v_lshlrev_b32_e32 v42, 16, v49
	v_and_b32_e32 v43, 0xffff0000, v49
	v_or_b32_e32 v48, 1, v102
	v_mov_b32_e32 v49, v81
	v_lshl_add_u64 v[48:49], s[62:63], 0, v[48:49]
	v_cndmask_b32_e64 v130, v52, 0, s[24:25]
	v_cndmask_b32_e64 v128, v53, 0, s[24:25]
	v_mad_u64_u32 v[52:53], s[26:27], v48, s68, v[82:83]
	v_mad_i32_i24 v53, v49, s68, v53
	v_lshl_add_u64 v[104:105], v[52:53], 0, s[56:57]
	v_or_b32_e32 v52, 2, v102
	v_mov_b32_e32 v53, v81
	v_lshl_add_u64 v[52:53], s[62:63], 0, v[52:53]
	v_cndmask_b32_e64 v110, v54, 0, s[24:25]
	v_cndmask_b32_e64 v66, v55, 0, s[24:25]
	v_mad_u64_u32 v[54:55], s[26:27], v52, s68, v[82:83]
	v_mad_i32_i24 v55, v53, s68, v55
	v_lshl_add_u64 v[106:107], v[54:55], 0, s[56:57]
	v_cndmask_b32_e64 v50, v44, 0, s[24:25]
	v_cndmask_b32_e64 v124, v51, 0, s[24:25]
	v_lshl_add_u64 v[48:49], v[104:105], 0, v[80:81]
	v_lshl_add_u64 v[52:53], v[106:107], 0, v[80:81]
	s_waitcnt vmcnt(3)
	v_mov_b32_e32 v118, v24
	v_mov_b32_e32 v119, v12
	v_mov_b32_e32 v51, v128
	v_cndmask_b32_e64 v74, v57, 0, s[24:25]
	v_cndmask_b32_e64 v72, v58, 0, s[24:25]
	v_cndmask_b32_e64 v70, v59, 0, s[24:25]
	v_cndmask_b32_e64 v64, v56, 0, s[24:25]
	v_lshlrev_b32_e32 v44, 16, v46
	global_load_dwordx4 v[56:59], v[48:49], off
	global_load_dwordx4 v[228:231], v[48:49], off offset:1024
	global_load_dwordx4 v[232:235], v[52:53], off offset:1024
	s_nop 0
	global_load_dwordx4 v[52:55], v[52:53], off
	v_or_b32_e32 v48, 3, v102
	v_mov_b32_e32 v49, v81
	v_pk_mul_f32 v[50:51], v[118:119], v[50:51]
	v_lshl_add_u64 v[48:49], s[62:63], 0, v[48:49]
	v_mov_b32_e32 v138, v16
	v_mov_b32_e32 v139, v20
	v_mov_b32_e32 v142, v74
	v_mov_b32_e32 v143, v44
	s_waitcnt vmcnt(6)
; __device__ __forceinline__ unsigned pk2(float lo, float hi) { f32x2_t v = {lo, hi}; bf16x2_t b = __builtin_convertvector(v, bf16x2_t); return __builtin_bit_cast(unsigned, b); }
; __device__ __forceinline__ float silu_f(float x) { return x * __builtin_amdgcn_rcpf(1.f + __builtin_amdgcn_exp2f(x * -1.4426950408889634f)); }
; __device__ __forceinline__ void conv4x8(const Params& p, int b, int c, int l0, int ch, float (&o)[4][8]) {
;     ...
; #pragma unroll
;     for (int k = 0; k < 4; ++k) {
; #pragma unroll
;         for (int j = 0; j < 8; ++j) o[k][j] = silu_f(cb[j] + w0[j] * r[k][j] + w1[j] * r[k + 1][j] + w2[j] * r[k + 2][j] + w3[j] * r[k + 3][j]);
;         uint4 ov; ov.x = pk2(o[k][0], o[k][1]); ov.y = pk2(o[k][2], o[k][3]); ov.z = pk2(o[k][4], o[k][5]); ov.w = pk2(o[k][6], o[k][7]);
;         *(uint4*)(xbc + (rowb + t0 + k) * 2048 + ch) = ov;
;         if (t0 + k >= 4093) {
;             float* dst = p.out + O_CP + ((size_t)b * 3 + (t0 + k - 4093)) * 2048 + ch;
;             *(float4*)dst = make_float4(r[k + 3][0], r[k + 3][1], r[k + 3][2], r[k + 3][3]); *(float4*)(dst + 4) = make_float4(r[k + 3][4], r[k + 3][5], r[k + 3][6], r[k + 3][7]);
;         }
	v_add_f32_e32 v50, v28, v50
	v_mad_u64_u32 v[108:109], s[26:27], v48, s68, v[82:83]
	v_pk_mul_f32 v[120:121], v[138:139], v[142:143]
	v_add_f32_e32 v50, v50, v51
	v_mad_i32_i24 v109, v49, s68, v109
	v_add_f32_e32 v50, v50, v120
	v_lshl_add_u64 v[108:109], v[108:109], 0, s[56:57]
	v_add_f32_e32 v87, v50, v121
	v_lshl_add_u64 v[48:49], v[108:109], 0, v[80:81]
	v_mul_f32_e32 v50, 0xbfb8aa3b, v87
	v_cndmask_b32_e64 v68, v63, 0, s[24:25]
	v_exp_f32_e32 v63, v50
	global_load_dwordx4 v[236:239], v[48:49], off offset:1024
	global_load_dwordx4 v[48:51], v[48:49], off
	v_mov_b32_e32 v140, v25
	v_mov_b32_e32 v141, v13
	v_add_f32_e32 v89, 1.0, v63
	v_mov_b32_e32 v63, v129
	v_cndmask_b32_e64 v112, v45, 0, s[24:25]
	v_and_b32_e32 v45, 0xffff0000, v46
	v_pk_mul_f32 v[62:63], v[140:141], v[62:63]
	v_mov_b32_e32 v144, v17
	v_mov_b32_e32 v145, v21
	v_mov_b32_e32 v120, v75
	v_mov_b32_e32 v121, v45
	v_add_f32_e32 v62, v29, v62
	v_pk_mul_f32 v[120:121], v[144:145], v[120:121]
	v_add_f32_e32 v62, v62, v63
	v_add_f32_e32 v62, v62, v120
	v_add_f32_e32 v91, v62, v121
	v_mul_f32_e32 v62, 0xbfb8aa3b, v91
	v_mov_b32_e32 v146, v26
	v_mov_b32_e32 v147, v14
	v_mov_b32_e32 v113, v110
	v_lshlrev_b32_e32 v46, 16, v47
	v_exp_f32_e32 v93, v62
	v_pk_mul_f32 v[62:63], v[146:147], v[112:113]
	v_mov_b32_e32 v148, v18
	v_mov_b32_e32 v149, v22
	v_mov_b32_e32 v152, v72
	v_mov_b32_e32 v153, v46
	v_add_f32_e32 v62, v30, v62
	v_pk_mul_f32 v[112:113], v[148:149], v[152:153]
	v_add_f32_e32 v62, v62, v63
	v_add_f32_e32 v62, v62, v112
	v_add_f32_e32 v103, v62, v113
	v_mul_f32_e32 v62, 0xbfb8aa3b, v103
	v_exp_f32_e32 v62, v62
	v_add_f32_e32 v63, 1.0, v93
	v_mov_b32_e32 v150, v27
	v_mov_b32_e32 v151, v15
	v_add_f32_e32 v62, 1.0, v62
	v_mov_b32_e32 v115, v111
	v_and_b32_e32 v47, 0xffff0000, v47
	v_rcp_f32_e32 v93, v63
	v_rcp_f32_e32 v117, v62
	v_pk_mul_f32 v[62:63], v[150:151], v[114:115]
	v_mov_b32_e32 v154, v19
	v_mov_b32_e32 v155, v23
	v_mov_b32_e32 v112, v73
	v_mov_b32_e32 v113, v47
	v_add_f32_e32 v62, v31, v62
	v_pk_mul_f32 v[112:113], v[154:155], v[112:113]
	v_add_f32_e32 v62, v62, v63
	v_add_f32_e32 v62, v62, v112
	v_add_f32_e32 v114, v62, v113
	v_mul_f32_e32 v62, 0xbfb8aa3b, v114
	v_exp_f32_e32 v62, v62
	v_rcp_f32_e32 v89, v89
	s_waitcnt vmcnt(7)
	v_mov_b32_e32 v156, v32
	v_mov_b32_e32 v157, v0
	v_add_f32_e32 v62, 1.0, v62
	v_mov_b32_e32 v125, v66
	v_mul_f32_e32 v122, v87, v89
	v_rcp_f32_e32 v89, v62
	v_pk_mul_f32 v[62:63], v[156:157], v[124:125]
	v_mov_b32_e32 v158, v4
	v_mov_b32_e32 v159, v8
	v_mov_b32_e32 v162, v70
	v_mov_b32_e32 v163, v40
	s_waitcnt vmcnt(6)
	v_add_f32_e32 v62, v36, v62
	v_pk_mul_f32 v[112:113], v[158:159], v[162:163]
	v_add_f32_e32 v62, v62, v63
	v_add_f32_e32 v62, v62, v112
	v_mul_f32_e32 v87, v91, v93
	v_add_f32_e32 v91, v62, v113
	v_mul_f32_e32 v62, 0xbfb8aa3b, v91
	v_mov_b32_e32 v160, v33
	v_mov_b32_e32 v161, v1
	v_mov_b32_e32 v127, v67
	v_exp_f32_e32 v93, v62
	v_pk_mul_f32 v[62:63], v[160:161], v[126:127]
	v_mov_b32_e32 v164, v5
	v_mov_b32_e32 v165, v9
	v_mov_b32_e32 v112, v71
	v_mov_b32_e32 v113, v41
	v_add_f32_e32 v62, v37, v62
	v_pk_mul_f32 v[112:113], v[164:165], v[112:113]
	v_add_f32_e32 v62, v62, v63
	v_add_f32_e32 v62, v62, v112
	v_mul_f32_e32 v120, v103, v117
	v_add_f32_e32 v103, v62, v113
	v_mul_f32_e32 v62, 0xbfb8aa3b, v103
	v_exp_f32_e32 v62, v62
	v_add_f32_e32 v63, 1.0, v93
	v_mov_b32_e32 v166, v34
	v_mov_b32_e32 v167, v2
	v_mov_b32_e32 v131, v64
	v_mul_f32_e32 v89, v114, v89
	v_rcp_f32_e32 v93, v63
	v_add_f32_e32 v114, 1.0, v62
	v_pk_mul_f32 v[62:63], v[166:167], v[130:131]
	v_mov_b32_e32 v168, v6
	v_mov_b32_e32 v169, v10
	v_mov_b32_e32 v182, v68
	v_mov_b32_e32 v183, v42
	v_add_f32_e32 v62, v38, v62
	v_pk_mul_f32 v[112:113], v[168:169], v[182:183]
	v_add_f32_e32 v62, v62, v63
	v_add_f32_e32 v62, v62, v112
	v_add_f32_e32 v115, v62, v113
	v_mul_f32_e32 v62, 0xbfb8aa3b, v115
	v_mov_b32_e32 v170, v35
	v_mov_b32_e32 v171, v3
	v_mov_b32_e32 v133, v65
	v_exp_f32_e32 v117, v62
	v_pk_mul_f32 v[62:63], v[170:171], v[132:133]
	v_mov_b32_e32 v184, v7
	v_mov_b32_e32 v185, v11
	v_mov_b32_e32 v112, v69
	v_mov_b32_e32 v113, v43
	v_add_f32_e32 v62, v39, v62
	v_pk_mul_f32 v[112:113], v[184:185], v[112:113]
	v_add_f32_e32 v62, v62, v63
	v_add_f32_e32 v62, v62, v112
	v_add_f32_e32 v62, v62, v113
	v_mul_f32_e32 v63, 0xbfb8aa3b, v62
	v_exp_f32_e32 v63, v63
	v_add_f32_e32 v113, 1.0, v117
	v_rcp_f32_e32 v112, v114
	v_rcp_f32_e32 v113, v113
	v_add_f32_e32 v63, 1.0, v63
	v_rcp_f32_e32 v63, v63
	v_mul_f32_e32 v126, v91, v93
	v_mul_f32_e32 v93, v103, v112
	v_mul_f32_e32 v124, v115, v113
	v_mul_f32_e32 v91, v62, v63
	v_lshl_add_u64 v[114:115], s[48:49], 0, v[60:61]
	v_cvt_pk_bf16_f32 v130, v122, v87
	v_cvt_pk_bf16_f32 v131, v120, v89
	v_cvt_pk_bf16_f32 v132, v126, v93
	v_cvt_pk_bf16_f32 v133, v124, v91
	v_lshl_add_u64 v[136:137], v[114:115], 0, v[80:81]
	v_add_u32_e32 v112, 0xfffff003, v102
	global_store_dwordx4 v[136:137], v[130:133], off
	s_and_saveexec_b64 s[26:27], s[28:29]
	s_cbranch_execz .LBB0_379
	s_load_dwordx2 s[30:31], s[42:43], 0xb0
	v_mov_b32_e32 v113, v81
	v_lshl_add_u64 v[60:61], s[64:65], 0, v[112:113]
	v_lshlrev_b64 v[60:61], 13, v[60:61]
	v_mov_b32_e32 v117, v81
	s_waitcnt lgkmcnt(0)
	v_lshl_add_u64 v[60:61], s[30:31], 0, v[60:61]
	v_lshl_add_u64 v[60:61], v[60:61], 0, v[116:117]
	v_lshl_add_u64 v[62:63], v[60:61], 0, s[58:59]
	v_add_co_u32_e32 v60, vcc, 0x8300000, v60
	s_nop 1
	v_addc_co_u32_e32 v61, vcc, 0, v61, vcc
	global_store_dwordx4 v[60:61], v[44:47], off
	global_store_dwordx4 v[62:63], v[40:43], off offset:16
